# NSA: unit prologue issues first window K block before waiting on Q rows; forced-block reference-max pass K loads hoisted to the start of top-k (3 blocks in flight under top-k and item-list build)
# baseline (speedup 1.0000x reference)
.LBB0_1257:
	v_bfe_u32 v228, v210, 2, 3
	s_mov_b64 s[4:5], s[0:1]
	v_or_b32_e32 v1, s84, v228
	s_lshl_b32 s14, s44, 6
	s_load_dwordx2 s[8:9], s[4:5], 0xb0
	v_add_u32_e32 v223, s14, v1
	v_add_u32_e32 v22, s85, v223
	v_ashrrev_i32_e32 v23, 31, v22
	v_lshlrev_b64 v[6:7], 11, v[22:23]
	v_bfe_u32 v231, v210, 5, 1
	s_waitcnt lgkmcnt(0)
	v_lshl_add_u64 v[6:7], s[8:9], 0, v[6:7]
	v_lshlrev_b32_e32 v194, 7, v4
	v_lshl_add_u64 v[6:7], v[6:7], 0, v[194:195]
	v_lshlrev_b32_e32 v212, 4, v231
	v_mov_b32_e32 v213, v195
	v_lshl_add_u64 v[6:7], v[6:7], 0, v[212:213]
	v_lshl_add_u64 v[18:19], v[6:7], 0, s[30:31]
	v_add_co_u32_e32 v6, vcc, s67, v6
	v_and_b32_e32 v1, 31, v210
	s_nop 0
	v_addc_co_u32_e32 v7, vcc, 0, v7, vcc
	global_load_dwordx4 v[6:9], v[6:7], off
	s_nop 0
	global_load_dwordx4 v[10:13], v[18:19], off offset:32
	global_load_dwordx4 v[14:17], v[18:19], off offset:64
	s_nop 0
	global_load_dwordx4 v[18:21], v[18:19], off offset:96
	v_lshlrev_b64 v[24:25], 8, v[22:23]
	v_mov_b32_e32 v3, v195
	v_or_b32_e32 v230, s3, v1
	v_lshl_add_u64 v[24:25], s[8:9], 0, v[24:25]
	v_mul_lo_u32 v1, v230, s66
	v_lshl_add_u64 v[2:3], v[24:25], 0, v[2:3]
	s_mov_b64 s[12:13], 0xd000000
	v_add_u32_e32 v1, s91, v1
	v_add_co_u32_e32 v24, vcc, s65, v2
	v_add_u32_e32 v224, v1, v212
	s_nop 0
	v_addc_co_u32_e32 v25, vcc, 0, v3, vcc
	v_lshl_add_u64 v[2:3], v[2:3], 0, s[12:13]
	s_mov_b64 s[4:5], s[0:1]
	global_load_dword v213, v[2:3], off offset:64
	global_load_dword v209, v[24:25], off
	global_load_dword v1, v[2:3], off offset:128
	s_add_i32 s15, s44, -8
	s_cmp_gt_i32 s44, 7
	s_cselect_b32 s10, s15, 0
	v_and_b32_e32 v229, 63, v210
	v_lshlrev_b32_e32 v194, 4, v229
	v_or_b32_e32 v200, 0x1000, v194
	v_or_b32_e32 v202, 0x1400, v194
	v_or_b32_e32 v204, 0x1800, v194
	v_or_b32_e32 v206, 0x1c00, v194
	s_load_dwordx2 s[4:5], s[4:5], 0xb0
	s_waitcnt lgkmcnt(0)
	s_add_u32 s16, s4, s42
	s_addc_u32 s17, s5, s43
	s_ashr_i32 s11, s10, 31
	s_lshl_b64 s[12:13], s[10:11], 13
	s_add_u32 s11, s16, s12
	s_addc_u32 s17, s17, s13
	s_add_u32 s16, s11, 0x6e00000
	s_addc_u32 s17, s17, 0
	global_load_dwordx4 v[98:101], v194, s[16:17]
	global_load_dwordx4 v[102:105], v194, s[16:17] offset:1024
	global_load_dwordx4 v[106:109], v194, s[16:17] offset:2048
	global_load_dwordx4 v[110:113], v194, s[16:17] offset:3072
	global_load_dwordx4 v[114:117], v200, s[16:17]
	global_load_dwordx4 v[118:121], v202, s[16:17]
	global_load_dwordx4 v[122:125], v204, s[16:17]
	global_load_dwordx4 v[126:129], v206, s[16:17]
	v_lshrrev_b32_e32 v2, 3, v210
	v_and_b32_e32 v226, 4, v2
	s_waitcnt vmcnt(15)
	v_mul_f32_e32 v208, 0x3fb8aa3b, v5
	v_lshlrev_b64 v[198:199], 10, v[22:23]
	v_lshlrev_b32_e32 v196, 6, v4
	v_mov_b32_e32 v3, v195
	v_mov_b32_e32 v4, v195
	v_mov_b32_e32 v5, v195
	v_lshl_add_u32 v225, v227, 10, s62
	v_mov_b32_e32 v201, v195
	v_mov_b32_e32 v203, v195
	v_mov_b32_e32 v205, v195
	v_mov_b32_e32 v207, v195
	v_mov_b32_e32 v233, 0
	v_mov_b32_e32 v234, 0xff800000
	s_waitcnt vmcnt(14)
	ds_write_b128 v224, v[6:9]
	s_waitcnt vmcnt(13)
	ds_write_b128 v224, v[10:13] offset:32
	s_waitcnt vmcnt(12)
	ds_write_b128 v224, v[14:17] offset:64
	s_waitcnt vmcnt(11)
	ds_write_b128 v224, v[18:21] offset:96
	s_waitcnt lgkmcnt(0)
	v_mov_b32_e32 v16, v195
	v_mov_b32_e32 v17, v195
	v_mov_b32_e32 v6, v195
	v_mov_b32_e32 v7, v195
	s_add_i32 s96, s44, -2
	s_lshl_b32 s16, s15, 6
	s_add_i32 s17, s14, s84
	s_max_i32 s11, s10, s96
	v_subrev_u32_e32 v211, s16, v223
	s_add_i32 s16, s44, -7
	v_add_u32_e32 v2, s17, v228
	s_lshl_b32 s17, s10, 6
	s_add_u32 s4, s4, s88
	s_addc_u32 s5, s5, s89
	s_add_u32 s4, s4, s12
	v_subrev_u32_e32 v232, s17, v2
	s_addc_u32 s5, s5, s13
	v_mov_b32_e32 v2, v195
	v_mov_b32_e32 v8, v195
	v_mov_b32_e32 v9, v195
	v_mov_b32_e32 v10, v195
	v_mov_b32_e32 v11, v195
	v_mov_b32_e32 v12, v195
	v_mov_b32_e32 v13, v195
	v_mov_b32_e32 v14, v195
	v_mov_b32_e32 v15, v195
	v_mov_b64_e32 v[32:33], v[16:17]
	v_lshl_add_u64 v[214:215], s[4:5], 0, v[194:195]
	s_mov_b32 s17, s10
	v_mov_b64_e32 v[30:31], v[14:15]
	v_mov_b64_e32 v[28:29], v[12:13]
	v_mov_b64_e32 v[26:27], v[10:11]
	v_mov_b64_e32 v[24:25], v[8:9]
	v_mov_b64_e32 v[22:23], v[6:7]
	v_mov_b64_e32 v[20:21], v[4:5]
	v_mov_b64_e32 v[18:19], v[2:3]

.LBB0_1312:
	s_load_dwordx2 s[56:57], s[0:1], 0xb0
	s_add_i32 s58, s44, -1
	s_max_i32 s58, s58, 0
	s_lshl_b32 s58, s58, 13
	s_lshl_b32 s59, s44, 13
	s_waitcnt lgkmcnt(0)
	s_add_u32 s56, s56, s42
	s_addc_u32 s57, s57, s43
	s_add_u32 s56, s56, 0x3a00000
	s_addc_u32 s57, s57, 0
	s_add_u32 s60, s56, s59
	s_addc_u32 s61, s57, 0
	global_load_dwordx4 v[62:65], v194, s[60:61]
	global_load_dwordx4 v[54:57], v194, s[60:61] offset:1024
	global_load_dwordx4 v[38:41], v194, s[60:61] offset:2048
	global_load_dwordx4 v[34:37], v194, s[60:61] offset:3072
	global_load_dwordx4 v[46:49], v200, s[60:61]
	global_load_dwordx4 v[42:45], v202, s[60:61]
	global_load_dwordx4 v[58:61], v204, s[60:61]
	global_load_dwordx4 v[50:53], v206, s[60:61]
	s_add_u32 s60, s56, s58
	s_addc_u32 s61, s57, 0
	global_load_dwordx4 v[98:101], v194, s[60:61]
	global_load_dwordx4 v[102:105], v194, s[60:61] offset:1024
	global_load_dwordx4 v[106:109], v194, s[60:61] offset:2048
	global_load_dwordx4 v[110:113], v194, s[60:61] offset:3072
	global_load_dwordx4 v[114:117], v200, s[60:61]
	global_load_dwordx4 v[118:121], v202, s[60:61]
	global_load_dwordx4 v[122:125], v204, s[60:61]
	global_load_dwordx4 v[126:129], v206, s[60:61]
	global_load_dwordx4 v[130:133], v194, s[56:57]
	global_load_dwordx4 v[134:137], v194, s[56:57] offset:1024
	global_load_dwordx4 v[138:141], v194, s[56:57] offset:2048
	global_load_dwordx4 v[142:145], v194, s[56:57] offset:3072
	global_load_dwordx4 v[146:149], v200, s[56:57]
	global_load_dwordx4 v[150:153], v202, s[56:57]
	global_load_dwordx4 v[154:157], v204, s[56:57]
	global_load_dwordx4 v[158:161], v206, s[56:57]
	v_cmp_eq_u32_e64 s[10:11], 0, v229
	v_cmp_eq_u32_e32 vcc, s44, v229
	s_add_i32 s45, s44, -1
	v_or_b32_e32 v2, 64, v229
	s_or_b64 s[12:13], s[10:11], vcc
	v_cmp_eq_u32_e32 vcc, s45, v229
	s_add_i32 s5, s44, 0xffffffbf
	s_or_b64 s[12:13], s[12:13], vcc
	v_cmp_eq_u32_e32 vcc, s44, v2
	v_cmp_eq_u32_e64 s[14:15], s5, v229
	s_or_b64 s[14:15], vcc, s[14:15]
	s_waitcnt lgkmcnt(0)
	s_cmp_gt_i32 s44, 15
	s_cselect_b64 s[46:47], -1, 0
	s_cmp_lt_i32 s44, 16
	s_mov_b32 s4, 0
	v_cmp_lt_i32_e64 s[16:17], s44, v229
	v_cmp_ge_i32_e64 s[18:19], s44, v229
	v_lshl_add_u32 v1, v229, 2, 0
	v_cmp_lt_i32_e64 s[20:21], s44, v2
	v_cmp_ge_i32_e64 s[22:23], s44, v2
	s_mov_b64 s[52:53], -1
	s_cselect_b64 s[48:49], -1, 0
	s_branch .LBB0_1314

.LBB0_1389:
	s_waitcnt vmcnt(0) lgkmcnt(0)
	s_add_u32 s4, s16, s42
	s_addc_u32 s5, s17, s43
	s_add_u32 s48, s4, 0x3a00000
	s_addc_u32 s49, s5, 0
	s_waitcnt lgkmcnt(0)
	s_cmp_lt_i32 s44, 2
	v_mov_b32_e32 v1, 0xff800000
	s_mov_b32 s14, 3
	s_cselect_b64 s[18:19], -1, 0
	s_branch .LBB0_1392

.LBB0_1392:
	s_cmp_eq_u32 s14, 2
	s_cselect_b32 s4, s45, 0
	s_cmp_eq_u32 s14, 3
	s_cselect_b32 s26, s44, s4
	s_cmp_lt_i32 s26, 0
	s_cselect_b64 s[4:5], -1, 0
	s_cmp_eq_u32 s14, 1
	s_cselect_b64 s[12:13], -1, 0
	s_and_b64 s[12:13], s[12:13], s[18:19]
	s_or_b64 s[4:5], s[4:5], s[12:13]
	s_and_b64 vcc, exec, s[4:5]
	s_cbranch_vccnz .LBB0_1391
	s_cmp_eq_u32 s14, 3
	s_cbranch_scc1 .Lf2_go
	s_cmp_eq_u32 s14, 2
	s_cbranch_scc0 .Lf2_c
	v_mov_b64_e32 v[62:63], v[98:99]
	v_mov_b64_e32 v[64:65], v[100:101]
	v_mov_b64_e32 v[54:55], v[102:103]
	v_mov_b64_e32 v[56:57], v[104:105]
	v_mov_b64_e32 v[38:39], v[106:107]
	v_mov_b64_e32 v[40:41], v[108:109]
	v_mov_b64_e32 v[34:35], v[110:111]
	v_mov_b64_e32 v[36:37], v[112:113]
	v_mov_b64_e32 v[46:47], v[114:115]
	v_mov_b64_e32 v[48:49], v[116:117]
	v_mov_b64_e32 v[42:43], v[118:119]
	v_mov_b64_e32 v[44:45], v[120:121]
	v_mov_b64_e32 v[58:59], v[122:123]
	v_mov_b64_e32 v[60:61], v[124:125]
	v_mov_b64_e32 v[50:51], v[126:127]
	v_mov_b64_e32 v[52:53], v[128:129]
	s_branch .Lf2_go
.Lf2_c:
	v_mov_b64_e32 v[62:63], v[130:131]
	v_mov_b64_e32 v[64:65], v[132:133]
	v_mov_b64_e32 v[54:55], v[134:135]
	v_mov_b64_e32 v[56:57], v[136:137]
	v_mov_b64_e32 v[38:39], v[138:139]
	v_mov_b64_e32 v[40:41], v[140:141]
	v_mov_b64_e32 v[34:35], v[142:143]
	v_mov_b64_e32 v[36:37], v[144:145]
	v_mov_b64_e32 v[46:47], v[146:147]
	v_mov_b64_e32 v[48:49], v[148:149]
	v_mov_b64_e32 v[42:43], v[150:151]
	v_mov_b64_e32 v[44:45], v[152:153]
	v_mov_b64_e32 v[58:59], v[154:155]
	v_mov_b64_e32 v[60:61], v[156:157]
	v_mov_b64_e32 v[50:51], v[158:159]
	v_mov_b64_e32 v[52:53], v[160:161]
.Lf2_go:
	s_cmp_lt_i32 s26, s96
	s_mov_b64 s[12:13], -1
	s_cbranch_scc1 .LBB0_1395
	ds_read_b128 v[2:5], v224
	ds_read_b128 v[66:69], v224 offset:32
	ds_read_b128 v[70:73], v224 offset:64
	ds_read_b128 v[74:77], v224 offset:96
	s_lshl_b32 s4, s26, 6
	s_waitcnt vmcnt(7) lgkmcnt(3)
	v_mfma_f32_32x32x16_bf16 v[18:33], v[62:65], v[2:5], 0
	v_subrev_u32_e32 v6, s4, v223
	s_mov_b64 s[12:13], 0
	v_sub_u32_e32 v6, v6, v226
	v_lshl_add_u32 v94, v6, 2, v225
	ds_read2_b32 v[78:79], v94 offset0:53 offset1:54
	ds_read2_b32 v[80:81], v94 offset0:55 offset1:56
	ds_read2_b32 v[82:83], v94 offset0:61 offset1:62
	ds_read2_b32 v[84:85], v94 offset0:63 offset1:64
	ds_read2_b32 v[86:87], v94 offset0:37 offset1:38
	ds_read2_b32 v[88:89], v94 offset0:39 offset1:40
	ds_read2_b32 v[90:91], v94 offset0:45 offset1:46
	ds_read2_b32 v[92:93], v94 offset0:47 offset1:48
	s_waitcnt vmcnt(6) lgkmcnt(10)
	v_mfma_f32_32x32x16_bf16 v[18:33], v[54:57], v[66:69], v[18:33]
	s_waitcnt vmcnt(5) lgkmcnt(9)
	v_mfma_f32_32x32x16_bf16 v[18:33], v[38:41], v[70:73], v[18:33]
	s_waitcnt vmcnt(4) lgkmcnt(8)
	v_mfma_f32_32x32x16_bf16 v[18:33], v[34:37], v[74:77], v[18:33]
	s_waitcnt lgkmcnt(4)
	s_nop 10
	v_fmamk_f32 v6, v19, 0x3fb8aa3b, v84
	v_fmamk_f32 v19, v21, 0x3fb8aa3b, v82
	v_fmamk_f32 v21, v23, 0x3fb8aa3b, v80
	v_fmamk_f32 v23, v25, 0x3fb8aa3b, v78
	v_max_f32_e32 v25, 0xff800000, v6
	s_waitcnt vmcnt(3)
	v_mfma_f32_32x32x16_bf16 v[2:17], v[46:49], v[2:5], 0
	v_fmac_f32_e32 v85, 0x3fb8aa3b, v18
	v_fmac_f32_e32 v83, 0x3fb8aa3b, v20
	v_max3_f32 v18, v85, s68, v83
	v_fmac_f32_e32 v81, 0x3fb8aa3b, v22
	v_fmac_f32_e32 v79, 0x3fb8aa3b, v24
	s_waitcnt lgkmcnt(0)
	v_fmamk_f32 v27, v27, 0x3fb8aa3b, v92
	v_max3_f32 v19, v25, v19, v21
	s_waitcnt vmcnt(2)
	v_mfma_f32_32x32x16_bf16 v[2:17], v[42:45], v[66:69], v[2:17]
	v_max3_f32 v18, v18, v81, v79
	v_fmac_f32_e32 v93, 0x3fb8aa3b, v26
	v_fmac_f32_e32 v91, 0x3fb8aa3b, v28
	v_fmamk_f32 v29, v29, 0x3fb8aa3b, v90
	v_fmamk_f32 v31, v31, 0x3fb8aa3b, v88
	v_max3_f32 v19, v19, v23, v27
	v_max3_f32 v18, v18, v93, v91
	s_waitcnt vmcnt(1)
	v_mfma_f32_32x32x16_bf16 v[2:17], v[58:61], v[70:73], v[2:17]
	v_fmac_f32_e32 v89, 0x3fb8aa3b, v30
	v_fmac_f32_e32 v87, 0x3fb8aa3b, v32
	v_max3_f32 v23, v19, v29, v31
	v_max3_f32 v22, v18, v89, v87
	ds_read2_b32 v[18:19], v94 offset0:31 offset1:32
	ds_read2_b32 v[20:21], v94 offset0:29 offset1:30
	v_fmamk_f32 v33, v33, 0x3fb8aa3b, v86
	s_waitcnt vmcnt(0)
	v_mfma_f32_32x32x16_bf16 v[2:17], v[50:53], v[74:77], v[2:17]
	s_waitcnt lgkmcnt(1)
	s_nop 10
	v_fmamk_f32 v19, v2, 0x3fb8aa3b, v19
	v_fmac_f32_e32 v18, 0x3fb8aa3b, v3
	ds_read2_b32 v[2:3], v94 offset0:23 offset1:24
	s_waitcnt lgkmcnt(1)
	v_fmamk_f32 v4, v4, 0x3fb8aa3b, v21
	v_max3_f32 v19, v22, v19, v4
	v_fmac_f32_e32 v20, 0x3fb8aa3b, v5
	ds_read2_b32 v[4:5], v94 offset0:21 offset1:22
	v_max3_f32 v18, v23, v33, v18
	s_waitcnt lgkmcnt(1)
	v_fmac_f32_e32 v2, 0x3fb8aa3b, v7
	v_fmamk_f32 v6, v6, 0x3fb8aa3b, v3
	v_max3_f32 v18, v18, v20, v2
	ds_read2_b32 v[2:3], v94 offset0:15 offset1:16
	s_waitcnt lgkmcnt(1)
	v_fmamk_f32 v5, v8, 0x3fb8aa3b, v5
	v_max3_f32 v5, v19, v6, v5
	ds_read2_b32 v[6:7], v94 offset0:13 offset1:14
	v_fmac_f32_e32 v4, 0x3fb8aa3b, v9
	s_waitcnt lgkmcnt(1)
	v_fmac_f32_e32 v2, 0x3fb8aa3b, v11
	v_fmamk_f32 v8, v10, 0x3fb8aa3b, v3
	v_max3_f32 v9, v18, v4, v2
	ds_read2_b32 v[2:3], v94 offset0:7 offset1:8
	s_waitcnt lgkmcnt(1)
	v_fmamk_f32 v4, v12, 0x3fb8aa3b, v7
	v_max3_f32 v7, v5, v8, v4
	ds_read2_b32 v[4:5], v94 offset0:5 offset1:6
	v_fmac_f32_e32 v6, 0x3fb8aa3b, v13
	s_waitcnt lgkmcnt(1)
	v_fmamk_f32 v3, v14, 0x3fb8aa3b, v3
	v_fmac_f32_e32 v2, 0x3fb8aa3b, v15
	v_max3_f32 v2, v9, v6, v2
	s_waitcnt lgkmcnt(0)
	v_fmamk_f32 v5, v16, 0x3fb8aa3b, v5
	v_max3_f32 v3, v7, v3, v5
	v_fmac_f32_e32 v4, 0x3fb8aa3b, v17
	v_max3_f32 v2, v2, v4, v3
	v_mov_b32_e32 v3, v2
	s_nop 1
	v_permlane32_swap_b32_e32 v2, v3
